# on top of previous: first K-iteration of each GEMM unit peeled with inline-0 accumulator input (32 first-touch MFMAs), the 128 v_mov accumulator zeroing per unit removed
# speedup vs baseline: 1.0181x; 1.0039x over previous
.LBB0_220:
	s_ashr_i32 s19, s18, 31
	s_lshl_b64 s[26:27], s[18:19], 19
	s_add_u32 s26, s53, s26
	s_addc_u32 s27, s52, s27
	s_and_b64 s[46:47], s[6:7], exec
	s_cselect_b32 s9, s27, s43
	s_cselect_b32 s19, s26, s42
	s_ashr_i32 s17, s16, 31
	s_lshl_b64 s[46:47], s[16:17], 19
	s_add_u32 s80, s91, s46
	s_addc_u32 s81, s93, s47
	s_and_b64 s[46:47], s[6:7], exec
	s_cselect_b32 s17, s81, s11
	s_cselect_b32 s54, s80, s10
	s_add_u32 s62, s10, 0x100
	s_addc_u32 s63, s11, 0
	s_add_u32 s10, s42, 0xc000
	s_addc_u32 s11, s43, 0
	s_mov_b32 s67, -2
	s_add_u32 s42, s10, 0x4000
	s_addc_u32 s43, s11, 0
	s_cmp_eq_u32 s67, 12
	s_cselect_b32 s50, s19, s42
	s_cselect_b32 s51, s9, s43
	s_cselect_b32 s46, s54, s62
	s_cselect_b32 s47, s17, s63
	s_add_u32 s42, s50, 0x8000
	s_addc_u32 s43, s51, 0
	s_add_i32 s57, 0, 0x10000
	s_add_i32 s60, 0, 0x14000
	v_add_u32_e32 v70, s57, v199
	v_add_u32_e32 v158, s60, v199
	ds_read_b128 v[50:53], v70
	ds_read_b128 v[54:57], v70 offset:1024
	ds_read_b128 v[66:69], v70 offset:2048
	ds_read_b128 v[70:73], v70 offset:3072
	ds_read_b128 v[146:149], v158
	ds_read_b128 v[150:153], v158 offset:1024
	ds_read_b128 v[154:157], v158 offset:2048
	ds_read_b128 v[158:161], v158 offset:3072
	v_lshl_add_u64 v[188:189], s[10:11], 0, v[176:177]
	s_add_i32 m0, s45, 0xc000
	ds_read_b128 v[180:183], v241
	ds_read_b128 v[184:187], v241 offset:1024
	ds_read_b128 v[202:205], v241 offset:2048
	ds_read_b128 v[206:209], v241 offset:3072
	ds_read_b128 v[210:213], v241 offset:4096
	ds_read_b128 v[214:217], v241 offset:5120
	ds_read_b128 v[218:221], v241 offset:6144
	ds_read_b128 v[244:247], v241 offset:7168
	global_load_lds_dwordx4 v[188:189], off
	v_lshl_add_u64 v[188:189], s[10:11], 0, v[178:179]
	s_add_i32 m0, s45, 0xe000
	s_nop 0
	global_load_lds_dwordx4 v[188:189], off
	s_waitcnt vmcnt(8)
	s_waitcnt lgkmcnt(0)
	s_setprio 1
	s_barrier
	v_mfma_f32_16x16x32_bf16 v[142:145], v[50:53], v[180:183], 0
	v_mfma_f32_16x16x32_bf16 v[138:141], v[66:69], v[180:183], 0
	v_mfma_f32_16x16x32_bf16 v[126:129], v[50:53], v[202:205], 0
	v_mfma_f32_16x16x32_bf16 v[122:125], v[66:69], v[202:205], 0
	v_mfma_f32_16x16x32_bf16 v[110:113], v[50:53], v[210:213], 0
	v_mfma_f32_16x16x32_bf16 v[106:109], v[66:69], v[210:213], 0
	v_mfma_f32_16x16x32_bf16 v[94:97], v[50:53], v[218:221], 0
	v_mfma_f32_16x16x32_bf16 v[90:93], v[66:69], v[218:221], 0
	v_mfma_f32_16x16x32_bf16 v[142:145], v[54:57], v[184:187], v[142:145]
	v_mfma_f32_16x16x32_bf16 v[138:141], v[70:73], v[184:187], v[138:141]
	v_mfma_f32_16x16x32_bf16 v[126:129], v[54:57], v[206:209], v[126:129]
	v_mfma_f32_16x16x32_bf16 v[122:125], v[70:73], v[206:209], v[122:125]
	v_mfma_f32_16x16x32_bf16 v[110:113], v[54:57], v[214:217], v[110:113]
	v_mfma_f32_16x16x32_bf16 v[106:109], v[70:73], v[214:217], v[106:109]
	v_mfma_f32_16x16x32_bf16 v[94:97], v[54:57], v[244:247], v[94:97]
	v_mfma_f32_16x16x32_bf16 v[90:93], v[70:73], v[244:247], v[90:93]
	v_mfma_f32_16x16x32_bf16 v[134:137], v[146:149], v[180:183], 0
	v_mfma_f32_16x16x32_bf16 v[130:133], v[154:157], v[180:183], 0
	v_mfma_f32_16x16x32_bf16 v[118:121], v[146:149], v[202:205], 0
	v_mfma_f32_16x16x32_bf16 v[114:117], v[154:157], v[202:205], 0
	v_mfma_f32_16x16x32_bf16 v[102:105], v[146:149], v[210:213], 0
	v_mfma_f32_16x16x32_bf16 v[98:101], v[154:157], v[210:213], 0
	v_mfma_f32_16x16x32_bf16 v[86:89], v[146:149], v[218:221], 0
	v_mfma_f32_16x16x32_bf16 v[82:85], v[154:157], v[218:221], 0
	v_mfma_f32_16x16x32_bf16 v[134:137], v[150:153], v[184:187], v[134:137]
	v_mfma_f32_16x16x32_bf16 v[130:133], v[158:161], v[184:187], v[130:133]
	v_mfma_f32_16x16x32_bf16 v[118:121], v[150:153], v[206:209], v[118:121]
	v_mfma_f32_16x16x32_bf16 v[114:117], v[158:161], v[206:209], v[114:117]
	v_mfma_f32_16x16x32_bf16 v[102:105], v[150:153], v[214:217], v[102:105]
	v_mfma_f32_16x16x32_bf16 v[98:101], v[158:161], v[214:217], v[98:101]
	v_mfma_f32_16x16x32_bf16 v[86:89], v[150:153], v[244:247], v[86:89]
	v_mfma_f32_16x16x32_bf16 v[82:85], v[158:161], v[244:247], v[82:85]
	s_barrier
	s_setprio 0
	s_add_i32 s57, s57, s69
	v_lshl_add_u64 v[188:189], s[46:47], 0, v[164:165]
	s_mov_b32 m0, s57
	ds_read_b128 v[180:183], v241 offset:16384
	ds_read_b128 v[184:187], v241 offset:17408
	ds_read_b128 v[202:205], v241 offset:18432
	ds_read_b128 v[206:209], v241 offset:19456
	ds_read_b128 v[210:213], v241 offset:20480
	ds_read_b128 v[214:217], v241 offset:21504
	ds_read_b128 v[218:221], v241 offset:22528
	ds_read_b128 v[244:247], v241 offset:23552
	global_load_lds_dwordx4 v[188:189], off
	s_add_i32 m0, s57, 0x2000
	s_add_u32 s94, s46, 0x40000
	v_lshl_add_u64 v[222:223], s[46:47], 0, v[168:169]
	s_addc_u32 s95, s47, 0
	s_add_i32 s57, s60, s69
	global_load_lds_dwordx4 v[222:223], off
	v_lshl_add_u64 v[234:235], s[94:95], 0, v[164:165]
	s_mov_b32 m0, s57
	s_nop 0
	global_load_lds_dwordx4 v[234:235], off
	v_lshl_add_u64 v[234:235], s[94:95], 0, v[168:169]
	s_add_i32 m0, s57, 0x2000
	s_nop 0
	global_load_lds_dwordx4 v[234:235], off
	v_lshl_add_u64 v[234:235], s[50:51], 0, v[162:163]
	s_mov_b32 m0, s45
	s_nop 0
	global_load_lds_dwordx4 v[234:235], off
	v_lshl_add_u64 v[234:235], s[50:51], 0, v[166:167]
	s_mov_b32 m0, s3
	s_nop 0
	global_load_lds_dwordx4 v[234:235], off
	s_waitcnt vmcnt(8)
	s_waitcnt lgkmcnt(0)
	s_setprio 1
	s_barrier
	v_mfma_f32_16x16x32_bf16 v[78:81], v[50:53], v[180:183], 0
	v_mfma_f32_16x16x32_bf16 v[74:77], v[66:69], v[180:183], 0
	v_mfma_f32_16x16x32_bf16 v[46:49], v[50:53], v[202:205], 0
	v_mfma_f32_16x16x32_bf16 v[42:45], v[66:69], v[202:205], 0
	v_mfma_f32_16x16x32_bf16 v[30:33], v[50:53], v[210:213], 0
	v_mfma_f32_16x16x32_bf16 v[26:29], v[66:69], v[210:213], 0
	v_mfma_f32_16x16x32_bf16 v[14:17], v[50:53], v[218:221], 0
	v_mfma_f32_16x16x32_bf16 v[10:13], v[66:69], v[218:221], 0
	v_mfma_f32_16x16x32_bf16 v[78:81], v[54:57], v[184:187], v[78:81]
	v_mfma_f32_16x16x32_bf16 v[74:77], v[70:73], v[184:187], v[74:77]
	v_mfma_f32_16x16x32_bf16 v[46:49], v[54:57], v[206:209], v[46:49]
	v_mfma_f32_16x16x32_bf16 v[42:45], v[70:73], v[206:209], v[42:45]
	v_mfma_f32_16x16x32_bf16 v[30:33], v[54:57], v[214:217], v[30:33]
	v_mfma_f32_16x16x32_bf16 v[26:29], v[70:73], v[214:217], v[26:29]
	v_mfma_f32_16x16x32_bf16 v[14:17], v[54:57], v[244:247], v[14:17]
	v_mfma_f32_16x16x32_bf16 v[10:13], v[70:73], v[244:247], v[10:13]
	v_mfma_f32_16x16x32_bf16 v[38:41], v[146:149], v[202:205], 0
	v_mfma_f32_16x16x32_bf16 v[34:37], v[154:157], v[202:205], 0
	v_mfma_f32_16x16x32_bf16 v[22:25], v[146:149], v[210:213], 0
	v_mfma_f32_16x16x32_bf16 v[18:21], v[154:157], v[210:213], 0
	v_mfma_f32_16x16x32_bf16 v[6:9], v[146:149], v[218:221], 0
	v_mfma_f32_16x16x32_bf16 v[2:5], v[154:157], v[218:221], 0
	v_mfma_f32_16x16x32_bf16 v[50:53], v[146:149], v[180:183], 0
	v_mfma_f32_16x16x32_bf16 v[54:57], v[154:157], v[180:183], 0
	v_mfma_f32_16x16x32_bf16 v[38:41], v[150:153], v[206:209], v[38:41]
	v_mfma_f32_16x16x32_bf16 v[34:37], v[158:161], v[206:209], v[34:37]
	v_mfma_f32_16x16x32_bf16 v[22:25], v[150:153], v[214:217], v[22:25]
	v_mfma_f32_16x16x32_bf16 v[18:21], v[158:161], v[214:217], v[18:21]
	v_mfma_f32_16x16x32_bf16 v[6:9], v[150:153], v[244:247], v[6:9]
	v_mfma_f32_16x16x32_bf16 v[2:5], v[158:161], v[244:247], v[2:5]
	v_mfma_f32_16x16x32_bf16 v[50:53], v[150:153], v[184:187], v[50:53]
	v_mfma_f32_16x16x32_bf16 v[54:57], v[158:161], v[184:187], v[54:57]
	s_barrier
	s_setprio 0
	s_add_i32 s57, 0, 0x18000
	s_add_i32 s60, 0, 0x1c000
	v_add_u32_e32 v70, s57, v199
	v_add_u32_e32 v158, s60, v199
	ds_read_b128 v[58:61], v70
	ds_read_b128 v[62:65], v70 offset:1024
	ds_read_b128 v[66:69], v70 offset:2048
	ds_read_b128 v[70:73], v70 offset:3072
	ds_read_b128 v[146:149], v158
	ds_read_b128 v[150:153], v158 offset:1024
	ds_read_b128 v[154:157], v158 offset:2048
	ds_read_b128 v[158:161], v158 offset:3072
	s_add_u32 s50, s50, 0x4000
	s_addc_u32 s51, s51, 0
	s_mov_b32 m0, s31
	v_lshl_add_u64 v[234:235], s[50:51], 0, v[162:163]
	ds_read_b128 v[180:183], v241 offset:32768
	ds_read_b128 v[184:187], v241 offset:33792
	ds_read_b128 v[202:205], v241 offset:34816
	ds_read_b128 v[206:209], v241 offset:35840
	ds_read_b128 v[210:213], v241 offset:36864
	ds_read_b128 v[214:217], v241 offset:37888
	ds_read_b128 v[218:221], v241 offset:38912
	ds_read_b128 v[244:247], v241 offset:39936
	global_load_lds_dwordx4 v[234:235], off
	v_lshl_add_u64 v[234:235], s[50:51], 0, v[166:167]
	s_mov_b32 m0, s33
	s_nop 0
	global_load_lds_dwordx4 v[234:235], off
	s_waitcnt vmcnt(8)
	s_waitcnt lgkmcnt(0)
	s_setprio 1
	s_barrier
	v_mfma_f32_16x16x32_bf16 v[142:145], v[58:61], v[180:183], v[142:145]
	v_mfma_f32_16x16x32_bf16 v[138:141], v[66:69], v[180:183], v[138:141]
	v_mfma_f32_16x16x32_bf16 v[126:129], v[58:61], v[202:205], v[126:129]
	v_mfma_f32_16x16x32_bf16 v[122:125], v[66:69], v[202:205], v[122:125]
	v_mfma_f32_16x16x32_bf16 v[110:113], v[58:61], v[210:213], v[110:113]
	v_mfma_f32_16x16x32_bf16 v[106:109], v[66:69], v[210:213], v[106:109]
	v_mfma_f32_16x16x32_bf16 v[94:97], v[58:61], v[218:221], v[94:97]
	v_mfma_f32_16x16x32_bf16 v[90:93], v[66:69], v[218:221], v[90:93]
	v_mfma_f32_16x16x32_bf16 v[142:145], v[62:65], v[184:187], v[142:145]
	v_mfma_f32_16x16x32_bf16 v[138:141], v[70:73], v[184:187], v[138:141]
	v_mfma_f32_16x16x32_bf16 v[126:129], v[62:65], v[206:209], v[126:129]
	v_mfma_f32_16x16x32_bf16 v[122:125], v[70:73], v[206:209], v[122:125]
	v_mfma_f32_16x16x32_bf16 v[110:113], v[62:65], v[214:217], v[110:113]
	v_mfma_f32_16x16x32_bf16 v[106:109], v[70:73], v[214:217], v[106:109]
	v_mfma_f32_16x16x32_bf16 v[94:97], v[62:65], v[244:247], v[94:97]
	v_mfma_f32_16x16x32_bf16 v[90:93], v[70:73], v[244:247], v[90:93]
	v_mfma_f32_16x16x32_bf16 v[134:137], v[146:149], v[180:183], v[134:137]
	v_mfma_f32_16x16x32_bf16 v[130:133], v[154:157], v[180:183], v[130:133]
	v_mfma_f32_16x16x32_bf16 v[118:121], v[146:149], v[202:205], v[118:121]
	v_mfma_f32_16x16x32_bf16 v[114:117], v[154:157], v[202:205], v[114:117]
	v_mfma_f32_16x16x32_bf16 v[102:105], v[146:149], v[210:213], v[102:105]
	v_mfma_f32_16x16x32_bf16 v[98:101], v[154:157], v[210:213], v[98:101]
	v_mfma_f32_16x16x32_bf16 v[86:89], v[146:149], v[218:221], v[86:89]
	v_mfma_f32_16x16x32_bf16 v[82:85], v[154:157], v[218:221], v[82:85]
	v_mfma_f32_16x16x32_bf16 v[134:137], v[150:153], v[184:187], v[134:137]
	v_mfma_f32_16x16x32_bf16 v[130:133], v[158:161], v[184:187], v[130:133]
	v_mfma_f32_16x16x32_bf16 v[118:121], v[150:153], v[206:209], v[118:121]
	v_mfma_f32_16x16x32_bf16 v[114:117], v[158:161], v[206:209], v[114:117]
	v_mfma_f32_16x16x32_bf16 v[102:105], v[150:153], v[214:217], v[102:105]
	v_mfma_f32_16x16x32_bf16 v[98:101], v[158:161], v[214:217], v[98:101]
	v_mfma_f32_16x16x32_bf16 v[86:89], v[150:153], v[244:247], v[86:89]
	v_mfma_f32_16x16x32_bf16 v[82:85], v[158:161], v[244:247], v[82:85]
	s_barrier
	s_setprio 0
	s_add_i32 s50, s57, s69
	v_lshl_add_u64 v[188:189], v[188:189], 0, s[64:65]
	s_mov_b32 m0, s50
	ds_read_b128 v[180:183], v241 offset:49152
	ds_read_b128 v[184:187], v241 offset:50176
	ds_read_b128 v[202:205], v241 offset:51200
	ds_read_b128 v[206:209], v241 offset:52224
	ds_read_b128 v[210:213], v241 offset:53248
	ds_read_b128 v[214:217], v241 offset:54272
	ds_read_b128 v[218:221], v241 offset:55296
	ds_read_b128 v[244:247], v241 offset:56320
	global_load_lds_dwordx4 v[188:189], off
	s_add_i32 m0, s50, 0x2000
	s_add_u32 s46, s46, 0x40080
	v_lshl_add_u64 v[188:189], v[222:223], 0, s[64:65]
	s_addc_u32 s47, s47, 0
	s_add_i32 s50, s60, s69
	global_load_lds_dwordx4 v[188:189], off
	v_lshl_add_u64 v[188:189], s[46:47], 0, v[164:165]
	s_mov_b32 m0, s50
	s_nop 0
	global_load_lds_dwordx4 v[188:189], off
	v_lshl_add_u64 v[188:189], s[46:47], 0, v[168:169]
	s_add_i32 m0, s50, 0x2000
	s_nop 0
	global_load_lds_dwordx4 v[188:189], off
	v_lshl_add_u64 v[188:189], s[42:43], 0, v[162:163]
	s_mov_b32 m0, s29
	s_nop 0
	global_load_lds_dwordx4 v[188:189], off
	v_lshl_add_u64 v[188:189], s[42:43], 0, v[166:167]
	s_mov_b32 m0, s21
	s_nop 0
	global_load_lds_dwordx4 v[188:189], off
	s_waitcnt vmcnt(8)
	s_waitcnt lgkmcnt(0)
	s_setprio 1
	s_barrier
	v_mfma_f32_16x16x32_bf16 v[78:81], v[58:61], v[180:183], v[78:81]
	v_mfma_f32_16x16x32_bf16 v[74:77], v[66:69], v[180:183], v[74:77]
	v_mfma_f32_16x16x32_bf16 v[46:49], v[58:61], v[202:205], v[46:49]
	v_mfma_f32_16x16x32_bf16 v[42:45], v[66:69], v[202:205], v[42:45]
	v_mfma_f32_16x16x32_bf16 v[30:33], v[58:61], v[210:213], v[30:33]
	v_mfma_f32_16x16x32_bf16 v[26:29], v[66:69], v[210:213], v[26:29]
	v_mfma_f32_16x16x32_bf16 v[14:17], v[58:61], v[218:221], v[14:17]
	v_mfma_f32_16x16x32_bf16 v[10:13], v[66:69], v[218:221], v[10:13]
	v_mfma_f32_16x16x32_bf16 v[78:81], v[62:65], v[184:187], v[78:81]
	v_mfma_f32_16x16x32_bf16 v[74:77], v[70:73], v[184:187], v[74:77]
	v_mfma_f32_16x16x32_bf16 v[46:49], v[62:65], v[206:209], v[46:49]
	v_mfma_f32_16x16x32_bf16 v[42:45], v[70:73], v[206:209], v[42:45]
	v_mfma_f32_16x16x32_bf16 v[30:33], v[62:65], v[214:217], v[30:33]
	v_mfma_f32_16x16x32_bf16 v[26:29], v[70:73], v[214:217], v[26:29]
	v_mfma_f32_16x16x32_bf16 v[14:17], v[62:65], v[244:247], v[14:17]
	v_mfma_f32_16x16x32_bf16 v[10:13], v[70:73], v[244:247], v[10:13]
	v_mfma_f32_16x16x32_bf16 v[50:53], v[146:149], v[180:183], v[50:53]
	v_mfma_f32_16x16x32_bf16 v[62:65], v[150:153], v[184:187], v[50:53]
	v_mfma_f32_16x16x32_bf16 v[50:53], v[154:157], v[180:183], v[54:57]
	v_mfma_f32_16x16x32_bf16 v[38:41], v[146:149], v[202:205], v[38:41]
	v_mfma_f32_16x16x32_bf16 v[34:37], v[154:157], v[202:205], v[34:37]
	v_mfma_f32_16x16x32_bf16 v[22:25], v[146:149], v[210:213], v[22:25]
	v_mfma_f32_16x16x32_bf16 v[18:21], v[154:157], v[210:213], v[18:21]
	v_mfma_f32_16x16x32_bf16 v[6:9], v[146:149], v[218:221], v[6:9]
	v_mfma_f32_16x16x32_bf16 v[2:5], v[154:157], v[218:221], v[2:5]
	v_mfma_f32_16x16x32_bf16 v[58:61], v[158:161], v[184:187], v[50:53]
	v_mfma_f32_16x16x32_bf16 v[38:41], v[150:153], v[206:209], v[38:41]
	v_mfma_f32_16x16x32_bf16 v[34:37], v[158:161], v[206:209], v[34:37]
	v_mfma_f32_16x16x32_bf16 v[22:25], v[150:153], v[214:217], v[22:25]
	v_mfma_f32_16x16x32_bf16 v[18:21], v[158:161], v[214:217], v[18:21]
	v_mfma_f32_16x16x32_bf16 v[6:9], v[150:153], v[244:247], v[6:9]
	v_mfma_f32_16x16x32_bf16 v[2:5], v[158:161], v[244:247], v[2:5]
	s_barrier
	s_setprio 0
	s_add_i32 s67, s67, 2
	s_add_u32 s62, s62, 0x100
	s_addc_u32 s63, s63, 0
	s_add_u32 s10, s10, 0x10000
	s_addc_u32 s11, s11, 0
	s_cmp_gt_u32 s67, 13
	s_cbranch_scc1 .Lpeel_exit_r

.Lpeel_exit_r:
	s_and_b64 vcc, exec, s[12:13]
	s_cbranch_vccz .LBB0_224
	s_barrier

.LBB0_308:
	s_add_u32 s43, s8, s28
	s_addc_u32 s52, s9, s21
	s_add_u32 s53, s10, 0x100
	s_addc_u32 s63, s11, 0
	s_mov_b64 s[10:11], 0
	s_waitcnt lgkmcnt(0)
	s_waitcnt vmcnt(0)
	s_add_u32 vcc_lo, s10, 1
	s_addc_u32 vcc_hi, s11, 0
	s_add_u32 s46, s10, 2
	s_addc_u32 s47, s11, 0
	s_lshl_b64 s[48:49], s[46:47], s54
	s_add_u32 s11, s8, s48
	s_addc_u32 s48, s9, s49
	s_cmp_eq_u32 s94, s10
	s_cselect_b32 s50, s0, s11
	s_cselect_b32 s51, s1, s48
	s_cselect_b32 s48, s44, s53
	s_cselect_b32 s49, s45, s63
	s_add_u32 s10, s50, s14
	s_addc_u32 s11, s51, s15
	s_add_i32 s57, 0, 0x10000
	s_add_i32 s60, 0, 0x14000
	v_add_u32_e32 v70, s57, v197
	v_add_u32_e32 v94, s60, v197
	ds_read_b128 v[50:53], v70
	ds_read_b128 v[58:61], v70 offset:1024
	ds_read_b128 v[66:69], v70 offset:2048
	ds_read_b128 v[70:73], v70 offset:3072
	ds_read_b128 v[82:85], v94
	ds_read_b128 v[86:89], v94 offset:1024
	ds_read_b128 v[90:93], v94 offset:2048
	ds_read_b128 v[94:97], v94 offset:3072
	s_lshl_b64 vcc, vcc, s54
	s_add_u32 vcc_lo, s43, vcc_lo
	s_addc_u32 vcc_hi, s52, vcc_hi
	v_lshl_add_u64 v[214:215], vcc, 0, v[202:203]
	s_add_i32 m0, s61, 0xc000
	ds_read_b128 v[154:157], v221
	ds_read_b128 v[158:161], v221 offset:1024
	ds_read_b128 v[170:173], v221 offset:2048
	ds_read_b128 v[174:177], v221 offset:3072
	ds_read_b128 v[178:181], v221 offset:4096
	ds_read_b128 v[182:185], v221 offset:5120
	ds_read_b128 v[186:189], v221 offset:6144
	ds_read_b128 v[210:213], v221 offset:7168
	global_load_lds_dwordx4 v[214:215], off
	v_lshl_add_u64 v[214:215], vcc, 0, v[204:205]
	s_add_i32 m0, s61, 0xe000
	s_nop 0
	global_load_lds_dwordx4 v[214:215], off
	s_waitcnt vmcnt(8)
	s_waitcnt lgkmcnt(0)
	s_setprio 1
	s_barrier
	v_mfma_f32_16x16x32_bf16 v[166:169], v[50:53], v[154:157], 0
	v_mfma_f32_16x16x32_bf16 v[162:165], v[66:69], v[154:157], 0
	v_mfma_f32_16x16x32_bf16 v[150:153], v[50:53], v[170:173], 0
	v_mfma_f32_16x16x32_bf16 v[146:149], v[66:69], v[170:173], 0
	v_mfma_f32_16x16x32_bf16 v[142:145], v[50:53], v[178:181], 0
	v_mfma_f32_16x16x32_bf16 v[138:141], v[66:69], v[178:181], 0
	v_mfma_f32_16x16x32_bf16 v[134:137], v[50:53], v[186:189], 0
	v_mfma_f32_16x16x32_bf16 v[130:133], v[66:69], v[186:189], 0
	v_mfma_f32_16x16x32_bf16 v[166:169], v[58:61], v[158:161], v[166:169]
	v_mfma_f32_16x16x32_bf16 v[162:165], v[70:73], v[158:161], v[162:165]
	v_mfma_f32_16x16x32_bf16 v[150:153], v[58:61], v[174:177], v[150:153]
	v_mfma_f32_16x16x32_bf16 v[146:149], v[70:73], v[174:177], v[146:149]
	v_mfma_f32_16x16x32_bf16 v[142:145], v[58:61], v[182:185], v[142:145]
	v_mfma_f32_16x16x32_bf16 v[138:141], v[70:73], v[182:185], v[138:141]
	v_mfma_f32_16x16x32_bf16 v[134:137], v[58:61], v[210:213], v[134:137]
	v_mfma_f32_16x16x32_bf16 v[130:133], v[70:73], v[210:213], v[130:133]
	v_mfma_f32_16x16x32_bf16 v[126:129], v[82:85], v[154:157], 0
	v_mfma_f32_16x16x32_bf16 v[122:125], v[90:93], v[154:157], 0
	v_mfma_f32_16x16x32_bf16 v[118:121], v[82:85], v[170:173], 0
	v_mfma_f32_16x16x32_bf16 v[114:117], v[90:93], v[170:173], 0
	v_mfma_f32_16x16x32_bf16 v[110:113], v[82:85], v[178:181], 0
	v_mfma_f32_16x16x32_bf16 v[106:109], v[90:93], v[178:181], 0
	v_mfma_f32_16x16x32_bf16 v[102:105], v[82:85], v[186:189], 0
	v_mfma_f32_16x16x32_bf16 v[98:101], v[90:93], v[186:189], 0
	v_mfma_f32_16x16x32_bf16 v[126:129], v[86:89], v[158:161], v[126:129]
	v_mfma_f32_16x16x32_bf16 v[122:125], v[94:97], v[158:161], v[122:125]
	v_mfma_f32_16x16x32_bf16 v[118:121], v[86:89], v[174:177], v[118:121]
	v_mfma_f32_16x16x32_bf16 v[114:117], v[94:97], v[174:177], v[114:117]
	v_mfma_f32_16x16x32_bf16 v[110:113], v[86:89], v[182:185], v[110:113]
	v_mfma_f32_16x16x32_bf16 v[106:109], v[94:97], v[182:185], v[106:109]
	v_mfma_f32_16x16x32_bf16 v[102:105], v[86:89], v[210:213], v[102:105]
	v_mfma_f32_16x16x32_bf16 v[98:101], v[94:97], v[210:213], v[98:101]
	s_barrier
	s_setprio 0
	s_add_i32 s57, s57, s29
	v_lshl_add_u64 v[214:215], s[48:49], 0, v[190:191]
	s_mov_b32 m0, s57
	ds_read_b128 v[154:157], v221 offset:16384
	ds_read_b128 v[158:161], v221 offset:17408
	ds_read_b128 v[170:173], v221 offset:18432
	ds_read_b128 v[174:177], v221 offset:19456
	ds_read_b128 v[178:181], v221 offset:20480
	ds_read_b128 v[182:185], v221 offset:21504
	ds_read_b128 v[186:189], v221 offset:22528
	ds_read_b128 v[210:213], v221 offset:23552
	global_load_lds_dwordx4 v[214:215], off
	s_add_i32 m0, s57, 0x2000
	v_lshl_add_u64 v[216:217], s[48:49], 0, v[206:207]
	s_add_u32 s48, s48, s2
	s_addc_u32 s49, s49, 0
	s_add_i32 s57, s60, s29
	global_load_lds_dwordx4 v[216:217], off
	v_lshl_add_u64 v[218:219], s[48:49], 0, v[190:191]
	s_mov_b32 m0, s57
	v_lshl_add_u64 v[222:223], s[48:49], 0, v[206:207]
	global_load_lds_dwordx4 v[218:219], off
	s_add_i32 m0, s57, 0x2000
	v_lshl_add_u64 v[234:235], s[50:51], 0, v[202:203]
	global_load_lds_dwordx4 v[222:223], off
	s_mov_b32 m0, s61
	s_nop 0
	global_load_lds_dwordx4 v[234:235], off
	v_lshl_add_u64 v[234:235], s[50:51], 0, v[204:205]
	s_mov_b32 m0, s66
	s_nop 0
	global_load_lds_dwordx4 v[234:235], off
	s_waitcnt vmcnt(8)
	s_waitcnt lgkmcnt(0)
	s_setprio 1
	s_barrier
	v_mfma_f32_16x16x32_bf16 v[78:81], v[50:53], v[154:157], 0
	v_mfma_f32_16x16x32_bf16 v[74:77], v[66:69], v[154:157], 0
	v_mfma_f32_16x16x32_bf16 v[62:65], v[50:53], v[170:173], 0
	v_mfma_f32_16x16x32_bf16 v[54:57], v[66:69], v[170:173], 0
	v_mfma_f32_16x16x32_bf16 v[46:49], v[50:53], v[178:181], 0
	v_mfma_f32_16x16x32_bf16 v[42:45], v[66:69], v[178:181], 0
	v_mfma_f32_16x16x32_bf16 v[38:41], v[50:53], v[186:189], 0
	v_mfma_f32_16x16x32_bf16 v[34:37], v[66:69], v[186:189], 0
	v_mfma_f32_16x16x32_bf16 v[78:81], v[58:61], v[158:161], v[78:81]
	v_mfma_f32_16x16x32_bf16 v[74:77], v[70:73], v[158:161], v[74:77]
	v_mfma_f32_16x16x32_bf16 v[62:65], v[58:61], v[174:177], v[62:65]
	v_mfma_f32_16x16x32_bf16 v[54:57], v[70:73], v[174:177], v[54:57]
	v_mfma_f32_16x16x32_bf16 v[46:49], v[58:61], v[182:185], v[46:49]
	v_mfma_f32_16x16x32_bf16 v[42:45], v[70:73], v[182:185], v[42:45]
	v_mfma_f32_16x16x32_bf16 v[38:41], v[58:61], v[210:213], v[38:41]
	v_mfma_f32_16x16x32_bf16 v[34:37], v[70:73], v[210:213], v[34:37]
	v_mfma_f32_16x16x32_bf16 v[30:33], v[82:85], v[154:157], 0
	v_mfma_f32_16x16x32_bf16 v[26:29], v[90:93], v[154:157], 0
	v_mfma_f32_16x16x32_bf16 v[22:25], v[82:85], v[170:173], 0
	v_mfma_f32_16x16x32_bf16 v[18:21], v[90:93], v[170:173], 0
	v_mfma_f32_16x16x32_bf16 v[14:17], v[82:85], v[178:181], 0
	v_mfma_f32_16x16x32_bf16 v[10:13], v[90:93], v[178:181], 0
	v_mfma_f32_16x16x32_bf16 v[6:9], v[82:85], v[186:189], 0
	v_mfma_f32_16x16x32_bf16 v[2:5], v[90:93], v[186:189], 0
	v_mfma_f32_16x16x32_bf16 v[30:33], v[86:89], v[158:161], v[30:33]
	v_mfma_f32_16x16x32_bf16 v[26:29], v[94:97], v[158:161], v[26:29]
	v_mfma_f32_16x16x32_bf16 v[22:25], v[86:89], v[174:177], v[22:25]
	v_mfma_f32_16x16x32_bf16 v[18:21], v[94:97], v[174:177], v[18:21]
	v_mfma_f32_16x16x32_bf16 v[14:17], v[86:89], v[182:185], v[14:17]
	v_mfma_f32_16x16x32_bf16 v[10:13], v[94:97], v[182:185], v[10:13]
	v_mfma_f32_16x16x32_bf16 v[6:9], v[86:89], v[210:213], v[6:9]
	v_mfma_f32_16x16x32_bf16 v[2:5], v[94:97], v[210:213], v[2:5]
	s_barrier
	s_setprio 0
	s_add_i32 s57, 0, 0x18000
	s_add_i32 s60, 0, 0x1c000
	v_add_u32_e32 v70, s57, v197
	v_add_u32_e32 v94, s60, v197
	ds_read_b128 v[50:53], v70
	ds_read_b128 v[58:61], v70 offset:1024
	ds_read_b128 v[66:69], v70 offset:2048
	ds_read_b128 v[70:73], v70 offset:3072
	ds_read_b128 v[82:85], v94
	ds_read_b128 v[86:89], v94 offset:1024
	ds_read_b128 v[90:93], v94 offset:2048
	ds_read_b128 v[94:97], v94 offset:3072
	s_add_u32 s48, s50, s28
	s_addc_u32 s49, s51, s21
	s_mov_b32 m0, s67
	v_lshl_add_u64 v[234:235], s[48:49], 0, v[202:203]
	ds_read_b128 v[154:157], v221 offset:32768
	ds_read_b128 v[158:161], v221 offset:33792
	ds_read_b128 v[170:173], v221 offset:34816
	ds_read_b128 v[174:177], v221 offset:35840
	ds_read_b128 v[178:181], v221 offset:36864
	ds_read_b128 v[182:185], v221 offset:37888
	ds_read_b128 v[186:189], v221 offset:38912
	ds_read_b128 v[210:213], v221 offset:39936
	global_load_lds_dwordx4 v[234:235], off
	v_lshl_add_u64 v[234:235], s[48:49], 0, v[204:205]
	s_mov_b32 m0, s69
	s_nop 0
	global_load_lds_dwordx4 v[234:235], off
	s_waitcnt vmcnt(8)
	s_waitcnt lgkmcnt(0)
	s_setprio 1
	s_barrier
	v_mfma_f32_16x16x32_bf16 v[166:169], v[50:53], v[154:157], v[166:169]
	v_mfma_f32_16x16x32_bf16 v[162:165], v[66:69], v[154:157], v[162:165]
	v_mfma_f32_16x16x32_bf16 v[150:153], v[50:53], v[170:173], v[150:153]
	v_mfma_f32_16x16x32_bf16 v[146:149], v[66:69], v[170:173], v[146:149]
	v_mfma_f32_16x16x32_bf16 v[142:145], v[50:53], v[178:181], v[142:145]
	v_mfma_f32_16x16x32_bf16 v[138:141], v[66:69], v[178:181], v[138:141]
	v_mfma_f32_16x16x32_bf16 v[134:137], v[50:53], v[186:189], v[134:137]
	v_mfma_f32_16x16x32_bf16 v[130:133], v[66:69], v[186:189], v[130:133]
	v_mfma_f32_16x16x32_bf16 v[166:169], v[58:61], v[158:161], v[166:169]
	v_mfma_f32_16x16x32_bf16 v[162:165], v[70:73], v[158:161], v[162:165]
	v_mfma_f32_16x16x32_bf16 v[150:153], v[58:61], v[174:177], v[150:153]
	v_mfma_f32_16x16x32_bf16 v[146:149], v[70:73], v[174:177], v[146:149]
	v_mfma_f32_16x16x32_bf16 v[142:145], v[58:61], v[182:185], v[142:145]
	v_mfma_f32_16x16x32_bf16 v[138:141], v[70:73], v[182:185], v[138:141]
	v_mfma_f32_16x16x32_bf16 v[134:137], v[58:61], v[210:213], v[134:137]
	v_mfma_f32_16x16x32_bf16 v[130:133], v[70:73], v[210:213], v[130:133]
	v_mfma_f32_16x16x32_bf16 v[126:129], v[82:85], v[154:157], v[126:129]
	v_mfma_f32_16x16x32_bf16 v[122:125], v[90:93], v[154:157], v[122:125]
	v_mfma_f32_16x16x32_bf16 v[118:121], v[82:85], v[170:173], v[118:121]
	v_mfma_f32_16x16x32_bf16 v[114:117], v[90:93], v[170:173], v[114:117]
	v_mfma_f32_16x16x32_bf16 v[110:113], v[82:85], v[178:181], v[110:113]
	v_mfma_f32_16x16x32_bf16 v[106:109], v[90:93], v[178:181], v[106:109]
	v_mfma_f32_16x16x32_bf16 v[102:105], v[82:85], v[186:189], v[102:105]
	v_mfma_f32_16x16x32_bf16 v[98:101], v[90:93], v[186:189], v[98:101]
	v_mfma_f32_16x16x32_bf16 v[126:129], v[86:89], v[158:161], v[126:129]
	v_mfma_f32_16x16x32_bf16 v[122:125], v[94:97], v[158:161], v[122:125]
	v_mfma_f32_16x16x32_bf16 v[118:121], v[86:89], v[174:177], v[118:121]
	v_mfma_f32_16x16x32_bf16 v[114:117], v[94:97], v[174:177], v[114:117]
	v_mfma_f32_16x16x32_bf16 v[110:113], v[86:89], v[182:185], v[110:113]
	v_mfma_f32_16x16x32_bf16 v[106:109], v[94:97], v[182:185], v[106:109]
	v_mfma_f32_16x16x32_bf16 v[102:105], v[86:89], v[210:213], v[102:105]
	v_mfma_f32_16x16x32_bf16 v[98:101], v[94:97], v[210:213], v[98:101]
	s_barrier
	s_setprio 0
	s_add_i32 s48, s57, s29
	v_lshl_add_u64 v[214:215], v[214:215], 0, s[64:65]
	s_mov_b32 m0, s48
	ds_read_b128 v[154:157], v221 offset:49152
	ds_read_b128 v[158:161], v221 offset:50176
	ds_read_b128 v[170:173], v221 offset:51200
	ds_read_b128 v[174:177], v221 offset:52224
	ds_read_b128 v[178:181], v221 offset:53248
	ds_read_b128 v[182:185], v221 offset:54272
	ds_read_b128 v[186:189], v221 offset:55296
	ds_read_b128 v[210:213], v221 offset:56320
	global_load_lds_dwordx4 v[214:215], off
	v_lshl_add_u64 v[214:215], v[216:217], 0, s[64:65]
	s_add_i32 m0, s48, 0x2000
	s_add_i32 s48, s60, s29
	global_load_lds_dwordx4 v[214:215], off
	v_lshl_add_u64 v[214:215], v[218:219], 0, s[64:65]
	s_mov_b32 m0, s48
	s_nop 0
	global_load_lds_dwordx4 v[214:215], off
	v_lshl_add_u64 v[214:215], v[222:223], 0, s[64:65]
	s_add_i32 m0, s48, 0x2000
	s_nop 0
	global_load_lds_dwordx4 v[214:215], off
	v_lshl_add_u64 v[214:215], s[10:11], 0, v[202:203]
	s_mov_b32 m0, s89
	s_nop 0
	global_load_lds_dwordx4 v[214:215], off
	v_lshl_add_u64 v[214:215], s[10:11], 0, v[204:205]
	s_mov_b32 m0, s91
	s_nop 0
	global_load_lds_dwordx4 v[214:215], off
	s_waitcnt vmcnt(8)
	s_waitcnt lgkmcnt(0)
	s_setprio 1
	s_barrier
	v_mfma_f32_16x16x32_bf16 v[78:81], v[50:53], v[154:157], v[78:81]
	v_mfma_f32_16x16x32_bf16 v[74:77], v[66:69], v[154:157], v[74:77]
	v_mfma_f32_16x16x32_bf16 v[62:65], v[50:53], v[170:173], v[62:65]
	v_mfma_f32_16x16x32_bf16 v[54:57], v[66:69], v[170:173], v[54:57]
	v_mfma_f32_16x16x32_bf16 v[46:49], v[50:53], v[178:181], v[46:49]
	v_mfma_f32_16x16x32_bf16 v[42:45], v[66:69], v[178:181], v[42:45]
	v_mfma_f32_16x16x32_bf16 v[38:41], v[50:53], v[186:189], v[38:41]
	v_mfma_f32_16x16x32_bf16 v[34:37], v[66:69], v[186:189], v[34:37]
	v_mfma_f32_16x16x32_bf16 v[78:81], v[58:61], v[158:161], v[78:81]
	v_mfma_f32_16x16x32_bf16 v[74:77], v[70:73], v[158:161], v[74:77]
	v_mfma_f32_16x16x32_bf16 v[62:65], v[58:61], v[174:177], v[62:65]
	v_mfma_f32_16x16x32_bf16 v[54:57], v[70:73], v[174:177], v[54:57]
	v_mfma_f32_16x16x32_bf16 v[46:49], v[58:61], v[182:185], v[46:49]
	v_mfma_f32_16x16x32_bf16 v[42:45], v[70:73], v[182:185], v[42:45]
	v_mfma_f32_16x16x32_bf16 v[38:41], v[58:61], v[210:213], v[38:41]
	v_mfma_f32_16x16x32_bf16 v[34:37], v[70:73], v[210:213], v[34:37]
	v_mfma_f32_16x16x32_bf16 v[30:33], v[82:85], v[154:157], v[30:33]
	v_mfma_f32_16x16x32_bf16 v[26:29], v[90:93], v[154:157], v[26:29]
	v_mfma_f32_16x16x32_bf16 v[22:25], v[82:85], v[170:173], v[22:25]
	v_mfma_f32_16x16x32_bf16 v[18:21], v[90:93], v[170:173], v[18:21]
	v_mfma_f32_16x16x32_bf16 v[14:17], v[82:85], v[178:181], v[14:17]
	v_mfma_f32_16x16x32_bf16 v[10:13], v[90:93], v[178:181], v[10:13]
	v_mfma_f32_16x16x32_bf16 v[6:9], v[82:85], v[186:189], v[6:9]
	v_mfma_f32_16x16x32_bf16 v[2:5], v[90:93], v[186:189], v[2:5]
	v_mfma_f32_16x16x32_bf16 v[30:33], v[86:89], v[158:161], v[30:33]
	v_mfma_f32_16x16x32_bf16 v[26:29], v[94:97], v[158:161], v[26:29]
	v_mfma_f32_16x16x32_bf16 v[22:25], v[86:89], v[174:177], v[22:25]
	v_mfma_f32_16x16x32_bf16 v[18:21], v[94:97], v[174:177], v[18:21]
	v_mfma_f32_16x16x32_bf16 v[14:17], v[86:89], v[182:185], v[14:17]
	v_mfma_f32_16x16x32_bf16 v[10:13], v[94:97], v[182:185], v[10:13]
	v_mfma_f32_16x16x32_bf16 v[6:9], v[86:89], v[210:213], v[6:9]
	v_mfma_f32_16x16x32_bf16 v[2:5], v[94:97], v[210:213], v[2:5]
	s_barrier
	s_setprio 0
	s_add_u32 s53, s53, 0x100
	s_addc_u32 s63, s63, 0
	s_cmp_ge_u32 s46, s71
	s_mov_b64 s[10:11], s[46:47]
	s_cbranch_scc1 .Lpeel_exit_s

.Lpeel_exit_s:
	s_and_b64 vcc, exec, s[18:19]
	s_cbranch_vccz .LBB0_312
	s_barrier

.LBB0_461:
	s_ashr_i32 s19, s18, 31
	s_lshl_b64 s[26:27], s[18:19], 19
	s_add_u32 s26, s58, s26
	s_addc_u32 s27, s59, s27
	s_and_b64 s[44:45], s[4:5], exec
	s_cselect_b32 s19, s27, s51
	s_cselect_b32 s24, s26, s50
	s_ashr_i32 s17, s16, 31
	s_lshl_b64 s[44:45], s[16:17], 19
	s_add_u32 s44, s13, s44
	s_addc_u32 s45, s21, s45
	s_and_b64 s[48:49], s[4:5], exec
	s_cselect_b32 s17, s45, s1
	s_cselect_b32 s47, s44, s0
	s_add_u32 s48, s0, 0x100
	s_addc_u32 s49, s1, 0
	s_add_u32 s0, s50, 0xc000
	s_addc_u32 s1, s51, 0
	s_mov_b32 s82, -2
	s_add_u32 s50, s0, 0x4000
	s_addc_u32 s51, s1, 0
	s_cmp_eq_u32 s82, 12
	s_cselect_b32 s88, s24, s50
	s_cselect_b32 s89, s19, s51
	s_cselect_b32 s80, s47, s48
	s_cselect_b32 s81, s17, s49
	s_add_u32 s50, s88, 0x8000
	s_addc_u32 s51, s89, 0
	s_add_i32 s83, 0, 0x10000
	s_add_i32 s85, 0, 0x14000
	v_add_u32_e32 v94, s83, v165
	v_add_u32_e32 v164, s85, v165
	ds_read_b128 v[82:85], v94
	ds_read_b128 v[86:89], v94 offset:1024
	ds_read_b128 v[90:93], v94 offset:2048
	ds_read_b128 v[94:97], v94 offset:3072
	ds_read_b128 v[172:175], v164
	ds_read_b128 v[176:179], v164 offset:1024
	ds_read_b128 v[180:183], v164 offset:2048
	ds_read_b128 v[184:187], v164 offset:3072
	v_lshl_add_u64 v[168:169], s[0:1], 0, v[160:161]
	s_add_i32 m0, s29, 0xc000
	ds_read_b128 v[202:205], v167
	ds_read_b128 v[206:209], v167 offset:1024
	ds_read_b128 v[210:213], v167 offset:2048
	ds_read_b128 v[214:217], v167 offset:3072
	ds_read_b128 v[218:221], v167 offset:4096
	ds_read_b128 v[242:245], v167 offset:5120
	ds_read_b128 v[246:249], v167 offset:6144
	ds_read_b128 v[250:253], v167 offset:7168
	global_load_lds_dwordx4 v[168:169], off
	v_lshl_add_u64 v[168:169], s[0:1], 0, v[162:163]
	s_add_i32 m0, s29, 0xe000
	s_nop 0
	global_load_lds_dwordx4 v[168:169], off
	s_waitcnt vmcnt(8)
	s_waitcnt lgkmcnt(0)
	s_setprio 1
	s_barrier
	v_mfma_f32_16x16x32_bf16 v[142:145], v[82:85], v[202:205], 0
	v_mfma_f32_16x16x32_bf16 v[138:141], v[90:93], v[202:205], 0
	v_mfma_f32_16x16x32_bf16 v[126:129], v[82:85], v[210:213], 0
	v_mfma_f32_16x16x32_bf16 v[122:125], v[90:93], v[210:213], 0
	v_mfma_f32_16x16x32_bf16 v[110:113], v[82:85], v[218:221], 0
	v_mfma_f32_16x16x32_bf16 v[106:109], v[90:93], v[218:221], 0
	v_mfma_f32_16x16x32_bf16 v[78:81], v[82:85], v[246:249], 0
	v_mfma_f32_16x16x32_bf16 v[74:77], v[90:93], v[246:249], 0
	v_mfma_f32_16x16x32_bf16 v[142:145], v[86:89], v[206:209], v[142:145]
	v_mfma_f32_16x16x32_bf16 v[138:141], v[94:97], v[206:209], v[138:141]
	v_mfma_f32_16x16x32_bf16 v[126:129], v[86:89], v[214:217], v[126:129]
	v_mfma_f32_16x16x32_bf16 v[122:125], v[94:97], v[214:217], v[122:125]
	v_mfma_f32_16x16x32_bf16 v[110:113], v[86:89], v[242:245], v[110:113]
	v_mfma_f32_16x16x32_bf16 v[106:109], v[94:97], v[242:245], v[106:109]
	v_mfma_f32_16x16x32_bf16 v[78:81], v[86:89], v[250:253], v[78:81]
	v_mfma_f32_16x16x32_bf16 v[74:77], v[94:97], v[250:253], v[74:77]
	v_mfma_f32_16x16x32_bf16 v[134:137], v[172:175], v[202:205], 0
	v_mfma_f32_16x16x32_bf16 v[130:133], v[180:183], v[202:205], 0
	v_mfma_f32_16x16x32_bf16 v[118:121], v[172:175], v[210:213], 0
	v_mfma_f32_16x16x32_bf16 v[114:117], v[180:183], v[210:213], 0
	v_mfma_f32_16x16x32_bf16 v[102:105], v[172:175], v[218:221], 0
	v_mfma_f32_16x16x32_bf16 v[98:101], v[180:183], v[218:221], 0
	v_mfma_f32_16x16x32_bf16 v[70:73], v[172:175], v[246:249], 0
	v_mfma_f32_16x16x32_bf16 v[66:69], v[180:183], v[246:249], 0
	v_mfma_f32_16x16x32_bf16 v[134:137], v[176:179], v[206:209], v[134:137]
	v_mfma_f32_16x16x32_bf16 v[130:133], v[184:187], v[206:209], v[130:133]
	v_mfma_f32_16x16x32_bf16 v[118:121], v[176:179], v[214:217], v[118:121]
	v_mfma_f32_16x16x32_bf16 v[114:117], v[184:187], v[214:217], v[114:117]
	v_mfma_f32_16x16x32_bf16 v[102:105], v[176:179], v[242:245], v[102:105]
	v_mfma_f32_16x16x32_bf16 v[98:101], v[184:187], v[242:245], v[98:101]
	v_mfma_f32_16x16x32_bf16 v[70:73], v[176:179], v[250:253], v[70:73]
	v_mfma_f32_16x16x32_bf16 v[66:69], v[184:187], v[250:253], v[66:69]
	s_barrier
	s_setprio 0
	s_add_i32 s83, s83, s28
	v_lshl_add_u64 v[168:169], s[80:81], 0, v[148:149]
	s_mov_b32 m0, s83
	ds_read_b128 v[202:205], v167 offset:16384
	ds_read_b128 v[206:209], v167 offset:17408
	ds_read_b128 v[210:213], v167 offset:18432
	ds_read_b128 v[214:217], v167 offset:19456
	ds_read_b128 v[218:221], v167 offset:20480
	ds_read_b128 v[242:245], v167 offset:21504
	ds_read_b128 v[246:249], v167 offset:22528
	ds_read_b128 v[250:253], v167 offset:23552
	global_load_lds_dwordx4 v[168:169], off
	s_add_i32 m0, s83, 0x2000
	s_add_u32 s94, s80, 0x40000
	v_lshl_add_u64 v[188:189], s[80:81], 0, v[152:153]
	s_addc_u32 s95, s81, 0
	s_add_i32 s83, s85, s28
	global_load_lds_dwordx4 v[188:189], off
	v_lshl_add_u64 v[222:223], s[94:95], 0, v[148:149]
	s_mov_b32 m0, s83
	s_nop 0
	global_load_lds_dwordx4 v[222:223], off
	v_lshl_add_u64 v[222:223], s[94:95], 0, v[152:153]
	s_add_i32 m0, s83, 0x2000
	s_nop 0
	global_load_lds_dwordx4 v[222:223], off
	v_lshl_add_u64 v[222:223], s[88:89], 0, v[146:147]
	s_mov_b32 m0, s29
	s_nop 0
	global_load_lds_dwordx4 v[222:223], off
	v_lshl_add_u64 v[222:223], s[88:89], 0, v[150:151]
	s_mov_b32 m0, s31
	s_nop 0
	global_load_lds_dwordx4 v[222:223], off
	s_waitcnt vmcnt(8)
	s_waitcnt lgkmcnt(0)
	s_setprio 1
	s_barrier
	v_mfma_f32_16x16x32_bf16 v[62:65], v[82:85], v[202:205], 0
	v_mfma_f32_16x16x32_bf16 v[58:61], v[90:93], v[202:205], 0
	v_mfma_f32_16x16x32_bf16 v[46:49], v[82:85], v[210:213], 0
	v_mfma_f32_16x16x32_bf16 v[42:45], v[90:93], v[210:213], 0
	v_mfma_f32_16x16x32_bf16 v[30:33], v[82:85], v[218:221], 0
	v_mfma_f32_16x16x32_bf16 v[26:29], v[90:93], v[218:221], 0
	v_mfma_f32_16x16x32_bf16 v[14:17], v[82:85], v[246:249], 0
	v_mfma_f32_16x16x32_bf16 v[10:13], v[90:93], v[246:249], 0
	v_mfma_f32_16x16x32_bf16 v[62:65], v[86:89], v[206:209], v[62:65]
	v_mfma_f32_16x16x32_bf16 v[58:61], v[94:97], v[206:209], v[58:61]
	v_mfma_f32_16x16x32_bf16 v[46:49], v[86:89], v[214:217], v[46:49]
	v_mfma_f32_16x16x32_bf16 v[42:45], v[94:97], v[214:217], v[42:45]
	v_mfma_f32_16x16x32_bf16 v[30:33], v[86:89], v[242:245], v[30:33]
	v_mfma_f32_16x16x32_bf16 v[26:29], v[94:97], v[242:245], v[26:29]
	v_mfma_f32_16x16x32_bf16 v[14:17], v[86:89], v[250:253], v[14:17]
	v_mfma_f32_16x16x32_bf16 v[10:13], v[94:97], v[250:253], v[10:13]
	v_mfma_f32_16x16x32_bf16 v[54:57], v[172:175], v[202:205], 0
	v_mfma_f32_16x16x32_bf16 v[50:53], v[180:183], v[202:205], 0
	v_mfma_f32_16x16x32_bf16 v[38:41], v[172:175], v[210:213], 0
	v_mfma_f32_16x16x32_bf16 v[34:37], v[180:183], v[210:213], 0
	v_mfma_f32_16x16x32_bf16 v[22:25], v[172:175], v[218:221], 0
	v_mfma_f32_16x16x32_bf16 v[18:21], v[180:183], v[218:221], 0
	v_mfma_f32_16x16x32_bf16 v[6:9], v[172:175], v[246:249], 0
	v_mfma_f32_16x16x32_bf16 v[2:5], v[180:183], v[246:249], 0
	v_mfma_f32_16x16x32_bf16 v[54:57], v[176:179], v[206:209], v[54:57]
	v_mfma_f32_16x16x32_bf16 v[50:53], v[184:187], v[206:209], v[50:53]
	v_mfma_f32_16x16x32_bf16 v[38:41], v[176:179], v[214:217], v[38:41]
	v_mfma_f32_16x16x32_bf16 v[34:37], v[184:187], v[214:217], v[34:37]
	v_mfma_f32_16x16x32_bf16 v[22:25], v[176:179], v[242:245], v[22:25]
	v_mfma_f32_16x16x32_bf16 v[18:21], v[184:187], v[242:245], v[18:21]
	v_mfma_f32_16x16x32_bf16 v[6:9], v[176:179], v[250:253], v[6:9]
	v_mfma_f32_16x16x32_bf16 v[2:5], v[184:187], v[250:253], v[2:5]
	s_barrier
	s_setprio 0
	s_add_i32 s83, 0, 0x18000
	s_add_i32 s85, 0, 0x1c000
	v_add_u32_e32 v94, s83, v165
	v_add_u32_e32 v164, s85, v165
	ds_read_b128 v[82:85], v94
	ds_read_b128 v[86:89], v94 offset:1024
	ds_read_b128 v[90:93], v94 offset:2048
	ds_read_b128 v[94:97], v94 offset:3072
	ds_read_b128 v[172:175], v164
	ds_read_b128 v[176:179], v164 offset:1024
	ds_read_b128 v[180:183], v164 offset:2048
	ds_read_b128 v[184:187], v164 offset:3072
	s_add_u32 s88, s88, 0x4000
	s_addc_u32 s89, s89, 0
	s_mov_b32 m0, s33
	v_lshl_add_u64 v[222:223], s[88:89], 0, v[146:147]
	ds_read_b128 v[202:205], v167 offset:32768
	ds_read_b128 v[206:209], v167 offset:33792
	ds_read_b128 v[210:213], v167 offset:34816
	ds_read_b128 v[214:217], v167 offset:35840
	ds_read_b128 v[218:221], v167 offset:36864
	ds_read_b128 v[242:245], v167 offset:37888
	ds_read_b128 v[246:249], v167 offset:38912
	ds_read_b128 v[250:253], v167 offset:39936
	global_load_lds_dwordx4 v[222:223], off
	v_lshl_add_u64 v[222:223], s[88:89], 0, v[150:151]
	s_mov_b32 m0, s36
	s_nop 0
	global_load_lds_dwordx4 v[222:223], off
	s_waitcnt vmcnt(8)
	s_waitcnt lgkmcnt(0)
	s_setprio 1
	s_barrier
	v_mfma_f32_16x16x32_bf16 v[142:145], v[82:85], v[202:205], v[142:145]
	v_mfma_f32_16x16x32_bf16 v[138:141], v[90:93], v[202:205], v[138:141]
	v_mfma_f32_16x16x32_bf16 v[126:129], v[82:85], v[210:213], v[126:129]
	v_mfma_f32_16x16x32_bf16 v[122:125], v[90:93], v[210:213], v[122:125]
	v_mfma_f32_16x16x32_bf16 v[110:113], v[82:85], v[218:221], v[110:113]
	v_mfma_f32_16x16x32_bf16 v[106:109], v[90:93], v[218:221], v[106:109]
	v_mfma_f32_16x16x32_bf16 v[78:81], v[82:85], v[246:249], v[78:81]
	v_mfma_f32_16x16x32_bf16 v[74:77], v[90:93], v[246:249], v[74:77]
	v_mfma_f32_16x16x32_bf16 v[142:145], v[86:89], v[206:209], v[142:145]
	v_mfma_f32_16x16x32_bf16 v[138:141], v[94:97], v[206:209], v[138:141]
	v_mfma_f32_16x16x32_bf16 v[126:129], v[86:89], v[214:217], v[126:129]
	v_mfma_f32_16x16x32_bf16 v[122:125], v[94:97], v[214:217], v[122:125]
	v_mfma_f32_16x16x32_bf16 v[110:113], v[86:89], v[242:245], v[110:113]
	v_mfma_f32_16x16x32_bf16 v[106:109], v[94:97], v[242:245], v[106:109]
	v_mfma_f32_16x16x32_bf16 v[78:81], v[86:89], v[250:253], v[78:81]
	v_mfma_f32_16x16x32_bf16 v[74:77], v[94:97], v[250:253], v[74:77]
	v_mfma_f32_16x16x32_bf16 v[134:137], v[172:175], v[202:205], v[134:137]
	v_mfma_f32_16x16x32_bf16 v[130:133], v[180:183], v[202:205], v[130:133]
	v_mfma_f32_16x16x32_bf16 v[118:121], v[172:175], v[210:213], v[118:121]
	v_mfma_f32_16x16x32_bf16 v[114:117], v[180:183], v[210:213], v[114:117]
	v_mfma_f32_16x16x32_bf16 v[102:105], v[172:175], v[218:221], v[102:105]
	v_mfma_f32_16x16x32_bf16 v[98:101], v[180:183], v[218:221], v[98:101]
	v_mfma_f32_16x16x32_bf16 v[70:73], v[172:175], v[246:249], v[70:73]
	v_mfma_f32_16x16x32_bf16 v[66:69], v[180:183], v[246:249], v[66:69]
	v_mfma_f32_16x16x32_bf16 v[134:137], v[176:179], v[206:209], v[134:137]
	v_mfma_f32_16x16x32_bf16 v[130:133], v[184:187], v[206:209], v[130:133]
	v_mfma_f32_16x16x32_bf16 v[118:121], v[176:179], v[214:217], v[118:121]
	v_mfma_f32_16x16x32_bf16 v[114:117], v[184:187], v[214:217], v[114:117]
	v_mfma_f32_16x16x32_bf16 v[102:105], v[176:179], v[242:245], v[102:105]
	v_mfma_f32_16x16x32_bf16 v[98:101], v[184:187], v[242:245], v[98:101]
	v_mfma_f32_16x16x32_bf16 v[70:73], v[176:179], v[250:253], v[70:73]
	v_mfma_f32_16x16x32_bf16 v[66:69], v[184:187], v[250:253], v[66:69]
	s_barrier
	s_setprio 0
	s_add_i32 s83, s83, s28
	v_lshl_add_u64 v[168:169], v[168:169], 0, s[64:65]
	s_mov_b32 m0, s83
	ds_read_b128 v[202:205], v167 offset:49152
	ds_read_b128 v[206:209], v167 offset:50176
	ds_read_b128 v[210:213], v167 offset:51200
	ds_read_b128 v[214:217], v167 offset:52224
	ds_read_b128 v[218:221], v167 offset:53248
	ds_read_b128 v[242:245], v167 offset:54272
	ds_read_b128 v[246:249], v167 offset:55296
	ds_read_b128 v[250:253], v167 offset:56320
	global_load_lds_dwordx4 v[168:169], off
	s_add_i32 m0, s83, 0x2000
	s_add_u32 s80, s80, 0x40080
	v_lshl_add_u64 v[168:169], v[188:189], 0, s[64:65]
	s_addc_u32 s81, s81, 0
	s_add_i32 s83, s85, s28
	global_load_lds_dwordx4 v[168:169], off
	v_lshl_add_u64 v[168:169], s[80:81], 0, v[148:149]
	s_mov_b32 m0, s83
	s_nop 0
	global_load_lds_dwordx4 v[168:169], off
	v_lshl_add_u64 v[168:169], s[80:81], 0, v[152:153]
	s_add_i32 m0, s83, 0x2000
	s_nop 0
	global_load_lds_dwordx4 v[168:169], off
	v_lshl_add_u64 v[168:169], s[50:51], 0, v[146:147]
	s_mov_b32 m0, s53
	s_nop 0
	global_load_lds_dwordx4 v[168:169], off
	v_lshl_add_u64 v[168:169], s[50:51], 0, v[150:151]
	s_mov_b32 m0, s54
	s_nop 0
	global_load_lds_dwordx4 v[168:169], off
	s_waitcnt vmcnt(8)
	s_waitcnt lgkmcnt(0)
	s_setprio 1
	s_barrier
	v_mfma_f32_16x16x32_bf16 v[62:65], v[82:85], v[202:205], v[62:65]
	v_mfma_f32_16x16x32_bf16 v[58:61], v[90:93], v[202:205], v[58:61]
	v_mfma_f32_16x16x32_bf16 v[46:49], v[82:85], v[210:213], v[46:49]
	v_mfma_f32_16x16x32_bf16 v[42:45], v[90:93], v[210:213], v[42:45]
	v_mfma_f32_16x16x32_bf16 v[30:33], v[82:85], v[218:221], v[30:33]
	v_mfma_f32_16x16x32_bf16 v[26:29], v[90:93], v[218:221], v[26:29]
	v_mfma_f32_16x16x32_bf16 v[14:17], v[82:85], v[246:249], v[14:17]
	v_mfma_f32_16x16x32_bf16 v[10:13], v[90:93], v[246:249], v[10:13]
	v_mfma_f32_16x16x32_bf16 v[62:65], v[86:89], v[206:209], v[62:65]
	v_mfma_f32_16x16x32_bf16 v[58:61], v[94:97], v[206:209], v[58:61]
	v_mfma_f32_16x16x32_bf16 v[46:49], v[86:89], v[214:217], v[46:49]
	v_mfma_f32_16x16x32_bf16 v[42:45], v[94:97], v[214:217], v[42:45]
	v_mfma_f32_16x16x32_bf16 v[30:33], v[86:89], v[242:245], v[30:33]
	v_mfma_f32_16x16x32_bf16 v[26:29], v[94:97], v[242:245], v[26:29]
	v_mfma_f32_16x16x32_bf16 v[14:17], v[86:89], v[250:253], v[14:17]
	v_mfma_f32_16x16x32_bf16 v[10:13], v[94:97], v[250:253], v[10:13]
	v_mfma_f32_16x16x32_bf16 v[54:57], v[172:175], v[202:205], v[54:57]
	v_mfma_f32_16x16x32_bf16 v[50:53], v[180:183], v[202:205], v[50:53]
	v_mfma_f32_16x16x32_bf16 v[38:41], v[172:175], v[210:213], v[38:41]
	v_mfma_f32_16x16x32_bf16 v[34:37], v[180:183], v[210:213], v[34:37]
	v_mfma_f32_16x16x32_bf16 v[22:25], v[172:175], v[218:221], v[22:25]
	v_mfma_f32_16x16x32_bf16 v[18:21], v[180:183], v[218:221], v[18:21]
	v_mfma_f32_16x16x32_bf16 v[6:9], v[172:175], v[246:249], v[6:9]
	v_mfma_f32_16x16x32_bf16 v[2:5], v[180:183], v[246:249], v[2:5]
	v_mfma_f32_16x16x32_bf16 v[54:57], v[176:179], v[206:209], v[54:57]
	v_mfma_f32_16x16x32_bf16 v[50:53], v[184:187], v[206:209], v[50:53]
	v_mfma_f32_16x16x32_bf16 v[38:41], v[176:179], v[214:217], v[38:41]
	v_mfma_f32_16x16x32_bf16 v[34:37], v[184:187], v[214:217], v[34:37]
	v_mfma_f32_16x16x32_bf16 v[22:25], v[176:179], v[242:245], v[22:25]
	v_mfma_f32_16x16x32_bf16 v[18:21], v[184:187], v[242:245], v[18:21]
	v_mfma_f32_16x16x32_bf16 v[6:9], v[176:179], v[250:253], v[6:9]
	v_mfma_f32_16x16x32_bf16 v[2:5], v[184:187], v[250:253], v[2:5]
	s_barrier
	s_setprio 0
	s_add_i32 s82, s82, 2
	s_add_u32 s48, s48, 0x100
	s_addc_u32 s49, s49, 0
	s_add_u32 s0, s0, 0x10000
	s_addc_u32 s1, s1, 0
	s_cmp_gt_u32 s82, 13
	s_cbranch_scc1 .Lpeel_exit_p

.Lpeel_exit_p:
	s_and_b64 vcc, exec, s[14:15]
	s_cbranch_vccz .LBB0_465
	s_barrier
